# LayerNorm phases: next-row prefetch no longer waited at the top of the row body (vmcnt moved to the cur=nxt copy)
# speedup vs baseline: 1.0030x; 1.0030x over previous
; DI void ln_phase(const bf16_t* __restrict__ y, const float* __restrict__ g, const float* __restrict__ b, bf16_t* __restrict__ xo, float* __restrict__ xf = nullptr) {
;     const int lane = threadIdx.x & 63, w = threadIdx.x >> 6;
;     const int gw = blockIdx.x * 4 + w, nw = gridDim.x * 4;
;     f32x4 gv[4], bv[4];
; #pragma unroll
;     for (int j = 0; j < 2; ++j) {
;         gv[2 * j] = *(const f32x4*)(g + 8 * (lane + 64 * j)); gv[2 * j + 1] = *(const f32x4*)(g + 8 * (lane + 64 * j) + 4);
;         bv[2 * j] = *(const f32x4*)(b + 8 * (lane + 64 * j)); bv[2 * j + 1] = *(const f32x4*)(b + 8 * (lane + 64 * j) + 4);
;     }
;     u32x4 cur[2], nxt[2];
;     if (gw < T_TOK) {
; #pragma unroll
;         for (int j = 0; j < 2; ++j) cur[j] = *(const u32x4*)(y + (size_t)gw * DM + 8 * (lane + 64 * j));
;     }
;     for (int row = gw; row < T_TOK; row += nw) {
.LBB0_347:
	s_or_b64 exec, exec, s[0:1]
	s_waitcnt lgkmcnt(0)
	v_lshlrev_b32_e32 v1, 3, v174
	v_and_b32_e32 v151, 0x1f8, v1
	v_add_u32_e32 v146, s26, v170
	v_mov_b32_e32 v51, 0
	v_lshlrev_b32_e32 v197, 2, v151
	v_lshlrev_b32_e32 v148, 1, v151
	v_ashrrev_i32_e32 v147, 31, v146
	s_barrier
	s_mov_b64 s[12:13], exec
	v_readlane_b32 s0, v253, 14
	v_readlane_b32 s1, v253, 15
	s_and_b64 s[0:1], s[12:13], s[0:1]
	s_mov_b64 exec, s[0:1]
	s_cbranch_execz .LBB0_352
	global_load_dwordx4 v[2:5], v197, s[48:49] offset:16
	global_load_dwordx4 v[6:9], v197, s[50:51] offset:16
	global_load_dwordx4 v[10:13], v197, s[48:49]
	global_load_dwordx4 v[14:17], v197, s[50:51]
	global_load_dwordx4 v[18:21], v197, s[48:49] offset:2064
	global_load_dwordx4 v[22:25], v197, s[50:51] offset:2064
	global_load_dwordx4 v[26:29], v197, s[48:49] offset:2048
	global_load_dwordx4 v[30:33], v197, s[50:51] offset:2048
	v_lshlrev_b64 v[34:35], 11, v[170:171]
	v_lshl_add_u64 v[52:53], s[90:91], 0, v[34:35]
	v_mov_b32_e32 v149, v51
	v_lshl_add_u64 v[34:35], v[52:53], 0, v[148:149]
	global_load_dwordx4 v[42:45], v[34:35], off
	global_load_dwordx4 v[46:49], v[34:35], off offset:1024
	s_ashr_i32 s27, s26, 31
	v_lshlrev_b64 v[34:35], 11, v[146:147]
	v_lshlrev_b32_e32 v50, 4, v172
	s_lshl_b64 s[14:15], s[26:27], 11
	v_lshl_add_u64 v[54:55], s[90:91], 0, v[34:35]
	s_mov_b64 s[16:17], 0
	s_mov_b32 s4, 0x10000
	s_mov_b32 s5, 0xffff
	v_mov_b32_e32 v1, 0x3727c5ac
	s_mov_b32 s20, 0x800000
	s_brev_b32 s21, 4
	v_mov_b32_e32 v56, v170
	s_waitcnt vmcnt(0)
	s_branch .LBB0_350
; DI unsigned pk_bf16(float a, float b) { f32x2 f = {a, b}; return __builtin_bit_cast(unsigned, __builtin_convertvector(f, bf16x2_t)); }
; DI float bf_lo(unsigned u) { return __uint_as_float(u << 16); }
; DI float bf_hi(unsigned u) { return __uint_as_float(u & 0xffff0000u); }
; DI void ln_phase(const bf16_t* __restrict__ y, const float* __restrict__ g, const float* __restrict__ b, bf16_t* __restrict__ xo, float* __restrict__ xf = nullptr) {
;     ...
;     for (int row = gw; row < T_TOK; row += nw) {
;         if (row + nw < T_TOK) {
; #pragma unroll
;             for (int j = 0; j < 2; ++j) nxt[j] = *(const u32x4*)(y + (size_t)(row + nw) * DM + 8 * (lane + 64 * j));
;         }
;         f32x4 v[4];
; #pragma unroll
;         for (int j = 0; j < 2; ++j) {
;             v[2 * j].x = bf_lo(cur[j].x); v[2 * j].y = bf_hi(cur[j].x); v[2 * j].z = bf_lo(cur[j].y); v[2 * j].w = bf_hi(cur[j].y);
;             v[2 * j + 1].x = bf_lo(cur[j].z); v[2 * j + 1].y = bf_hi(cur[j].z); v[2 * j + 1].z = bf_lo(cur[j].w); v[2 * j + 1].w = bf_hi(cur[j].w);
;         }
;         float s = 0.f;
; #pragma unroll
;         for (int i = 0; i < 4; ++i) s += (v[i].x + v[i].y) + (v[i].z + v[i].w);
;         const float mu = wave_sum(s) * (1.0f / DM);
;         float q = 0.f;
; #pragma unroll
;         for (int i = 0; i < 4; ++i) { const f32x4 d = v[i] - mu; q += (d.x * d.x + d.y * d.y) + (d.z * d.z + d.w * d.w); }
;         const float rstd = rsqrtf(wave_sum(q) * (1.0f / DM) + LN_EPS);
; #pragma unroll
;         for (int j = 0; j < 2; ++j) {
;             const f32x4 o0 = (v[2 * j] - mu) * rstd * gv[2 * j] + bv[2 * j], o1 = (v[2 * j + 1] - mu) * rstd * gv[2 * j + 1] + bv[2 * j + 1];
;             const size_t off = (size_t)row * DM + 8 * (lane + 64 * j);
;             if (xf) { *(f32x4*)(xf + off) = o0; *(f32x4*)(xf + off + 4) = o1; }
;             if (xo) { u32x4 wv = {pk_bf16(o0.x, o0.y), pk_bf16(o0.z, o0.w), pk_bf16(o1.x, o1.y), pk_bf16(o1.z, o1.w)}; *(u32x4*)(xo + off) = wv; }
;         }
; #pragma unroll
;         for (int j = 0; j < 2; ++j) cur[j] = nxt[j];
;     }
.LBB0_349:
	s_or_b64 exec, exec, s[18:19]
	v_lshlrev_b32_e32 v67, 16, v43
	v_lshlrev_b32_e32 v66, 16, v42
	v_and_b32_e32 v43, 0xffff0000, v43
	v_and_b32_e32 v42, 0xffff0000, v42
	v_pk_add_f32 v[68:69], v[66:67], v[42:43]
	v_lshlrev_b32_e32 v62, 16, v49
	v_and_b32_e32 v64, 0xffff0000, v49
	v_add_f32_e32 v49, v68, v69
	v_lshlrev_b32_e32 v69, 16, v45
	v_lshlrev_b32_e32 v68, 16, v44
	v_and_b32_e32 v45, 0xffff0000, v45
	v_and_b32_e32 v44, 0xffff0000, v44
	v_pk_add_f32 v[70:71], v[68:69], v[44:45]
	v_lshlrev_b32_e32 v58, 16, v46
	v_and_b32_e32 v59, 0xffff0000, v46
	v_lshlrev_b32_e32 v46, 16, v47
	v_and_b32_e32 v47, 0xffff0000, v47
	v_pk_add_f32 v[70:71], v[70:71], v[70:71] op_sel_hi:[0,1]
	v_lshlrev_b32_e32 v60, 16, v48
	v_and_b32_e32 v48, 0xffff0000, v48
	v_add_f32_e32 v65, 0, v49
	v_add_f32_e32 v61, v58, v59
	v_add_f32_e32 v49, v46, v47
	v_mov_b32_e32 v63, v71
	v_pk_add_f32 v[72:73], v[60:61], v[48:49]
	v_pk_add_f32 v[70:71], v[62:63], v[64:65]
	s_and_b64 s[18:19], exec, vcc
	v_pk_add_f32 v[70:71], v[72:73], v[70:71]
	s_or_b64 s[16:17], s[18:19], s[16:17]
	v_add_f32_e32 v49, v70, v71
	ds_bpermute_b32 v57, v173, v49
	v_lshl_add_u64 v[54:55], v[54:55], 0, s[14:15]
	s_waitcnt lgkmcnt(0)
	v_add_f32_e32 v49, v49, v57
	ds_bpermute_b32 v57, v175, v49
	s_waitcnt lgkmcnt(0)
	v_add_f32_e32 v49, v49, v57
	ds_bpermute_b32 v57, v192, v49
	s_waitcnt lgkmcnt(0)
	v_add_f32_e32 v49, v49, v57
	ds_bpermute_b32 v57, v193, v49
	s_waitcnt lgkmcnt(0)
	v_add_f32_e32 v49, v49, v57
	ds_bpermute_b32 v57, v194, v49
	s_waitcnt lgkmcnt(0)
	v_add_f32_e32 v49, v49, v57
	ds_bpermute_b32 v57, v195, v49
	s_waitcnt lgkmcnt(0)
	v_add_f32_e32 v49, v49, v57
	v_fmac_f32_e32 v42, 0xba800000, v49
	v_fmac_f32_e32 v43, 0xba800000, v49
	v_fmac_f32_e32 v67, 0xba800000, v49
	v_fmac_f32_e32 v66, 0xba800000, v49
	v_mov_b32_e32 v70, v67
	v_mov_b32_e32 v71, v43
	v_mov_b32_e32 v67, v42
	v_pk_mul_f32 v[72:73], v[70:71], v[70:71]
	v_pk_mul_f32 v[42:43], v[66:67], v[66:67]
	v_fmac_f32_e32 v44, 0xba800000, v49
	v_pk_mov_b32 v[74:75], v[42:43], v[72:73] op_sel:[1,0]
	v_mov_b32_e32 v43, v73
	v_fmac_f32_e32 v45, 0xba800000, v49
	v_fmac_f32_e32 v69, 0xba800000, v49
	v_pk_add_f32 v[42:43], v[74:75], v[42:43]
	v_fmac_f32_e32 v68, 0xba800000, v49
	v_mov_b32_e32 v72, v69
	v_mov_b32_e32 v73, v45
	v_mov_b32_e32 v69, v44
	v_pk_add_f32 v[42:43], v[42:43], v[42:43] op_sel_hi:[0,1]
	v_pk_mul_f32 v[74:75], v[72:73], v[72:73]
	v_pk_mul_f32 v[44:45], v[68:69], v[68:69]
	v_fmac_f32_e32 v58, 0xba800000, v49
	v_pk_mov_b32 v[76:77], v[44:45], v[74:75] op_sel:[1,0]
	v_mov_b32_e32 v45, v75
	v_fmac_f32_e32 v59, 0xba800000, v49
	v_fmac_f32_e32 v46, 0xba800000, v49
	v_mul_f32_e32 v42, v58, v58
	v_pk_add_f32 v[44:45], v[76:77], v[44:45]
	v_fmac_f32_e32 v47, 0xba800000, v49
	v_pk_fma_f32 v[74:75], v[58:59], v[58:59], v[42:43] op_sel_hi:[1,1,0]
	v_mul_f32_e32 v42, v46, v46
	v_pk_add_f32 v[44:45], v[44:45], v[44:45] op_sel_hi:[0,1]
	v_pk_fma_f32 v[76:77], v[46:47], v[46:47], v[42:43] op_sel_hi:[1,1,0]
	v_fmac_f32_e32 v64, 0xba800000, v49
	v_fmac_f32_e32 v62, 0xba800000, v49
	v_fmac_f32_e32 v48, 0xba800000, v49
	v_fmac_f32_e32 v60, 0xba800000, v49
	v_mul_f32_e32 v74, v60, v60
	v_mul_f32_e32 v76, v48, v48
	v_mul_f32_e32 v42, v62, v62
	v_mul_f32_e32 v44, v64, v64
	v_pk_add_f32 v[74:75], v[74:75], v[76:77]
	v_pk_add_f32 v[42:43], v[42:43], v[44:45]
	v_mov_b32_e32 v61, v48
	v_pk_add_f32 v[42:43], v[74:75], v[42:43]
	v_mov_b32_e32 v63, v64
	v_add_f32_e32 v42, v42, v43
	ds_bpermute_b32 v43, v173, v42
	s_waitcnt lgkmcnt(0)
	v_add_f32_e32 v42, v42, v43
	ds_bpermute_b32 v43, v175, v42
	s_waitcnt lgkmcnt(0)
	v_add_f32_e32 v42, v42, v43
	ds_bpermute_b32 v43, v192, v42
	s_waitcnt lgkmcnt(0)
	v_add_f32_e32 v42, v42, v43
	ds_bpermute_b32 v43, v193, v42
	s_waitcnt lgkmcnt(0)
	v_add_f32_e32 v42, v42, v43
	ds_bpermute_b32 v43, v194, v42
	s_waitcnt lgkmcnt(0)
	v_add_f32_e32 v42, v42, v43
	ds_bpermute_b32 v43, v195, v42
	s_waitcnt lgkmcnt(0)
	v_add_f32_e32 v42, v42, v43
	v_fmamk_f32 v42, v42, 0x3a800000, v1
	v_mul_f32_e32 v43, 0x4b800000, v42
	v_cmp_gt_f32_e64 s[0:1], s20, v42
	s_nop 1
	v_cndmask_b32_e64 v42, v42, v43, s[0:1]
	v_rsq_f32_e32 v42, v42
	s_nop 0
	v_mul_f32_e32 v43, 0x45800000, v42
	v_cndmask_b32_e64 v74, v42, v43, s[0:1]
	v_pk_mul_f32 v[42:43], v[66:67], v[74:75] op_sel_hi:[1,0]
	v_pk_mul_f32 v[44:45], v[70:71], v[74:75] op_sel_hi:[1,0]
	v_pk_mul_f32 v[66:67], v[68:69], v[74:75] op_sel_hi:[1,0]
	v_pk_fma_f32 v[44:45], v[12:13], v[44:45], v[16:17]
	v_pk_fma_f32 v[42:43], v[10:11], v[42:43], v[14:15]
	v_pk_fma_f32 v[66:67], v[2:3], v[66:67], v[6:7]
	v_pk_mul_f32 v[68:69], v[72:73], v[74:75] op_sel_hi:[1,0]
	v_cvt_pk_bf16_f32 v42, v42, v43
	v_cvt_pk_bf16_f32 v43, v44, v45
	v_cvt_pk_bf16_f32 v44, v66, v67
	v_lshl_add_u64 v[66:67], v[52:53], 0, v[50:51]
	v_pk_fma_f32 v[68:69], v[4:5], v[68:69], v[8:9]
	v_add_co_u32_e32 v66, vcc, s21, v66
	v_cvt_pk_bf16_f32 v45, v68, v69
	s_nop 0
	v_addc_co_u32_e32 v67, vcc, 0, v67, vcc
	global_store_dwordx4 v[66:67], v[42:45], off
	v_pk_mul_f32 v[48:49], v[62:63], v[74:75] op_sel_hi:[1,0]
	v_lshl_add_u64 v[52:53], v[52:53], 0, s[14:15]
	v_pk_mul_f32 v[42:43], v[58:59], v[74:75] op_sel_hi:[1,0]
	v_pk_mul_f32 v[44:45], v[46:47], v[74:75] op_sel_hi:[1,0]
	v_pk_mul_f32 v[46:47], v[60:61], v[74:75] op_sel_hi:[1,0]
	v_pk_fma_f32 v[44:45], v[28:29], v[44:45], v[32:33]
	v_pk_fma_f32 v[42:43], v[26:27], v[42:43], v[30:31]
	v_pk_fma_f32 v[48:49], v[20:21], v[48:49], v[24:25]
	v_pk_fma_f32 v[46:47], v[18:19], v[46:47], v[22:23]
	v_cvt_pk_bf16_f32 v42, v42, v43
	v_cvt_pk_bf16_f32 v43, v44, v45
	v_cvt_pk_bf16_f32 v44, v46, v47
	v_cvt_pk_bf16_f32 v45, v48, v49
	global_store_dwordx4 v[66:67], v[42:45], off offset:1024
	s_waitcnt vmcnt(2)
	v_mov_b32_e32 v46, v34
	v_mov_b32_e32 v47, v35
	v_mov_b32_e32 v42, v38
	v_mov_b32_e32 v43, v39
	v_mov_b32_e32 v44, v40
	v_mov_b32_e32 v45, v41
	v_mov_b32_e32 v48, v36
	v_mov_b32_e32 v49, v37
	s_andn2_b64 exec, exec, s[16:17]
	s_cbranch_execz .LBB0_352

; DI void ln_phase(const bf16_t* __restrict__ y, const float* __restrict__ g, const float* __restrict__ b, bf16_t* __restrict__ xo, float* __restrict__ xf = nullptr) {
;     const int lane = threadIdx.x & 63, w = threadIdx.x >> 6;
;     const int gw = blockIdx.x * 4 + w, nw = gridDim.x * 4;
;     f32x4 gv[4], bv[4];
; #pragma unroll
;     for (int j = 0; j < 2; ++j) {
;         gv[2 * j] = *(const f32x4*)(g + 8 * (lane + 64 * j)); gv[2 * j + 1] = *(const f32x4*)(g + 8 * (lane + 64 * j) + 4);
;         bv[2 * j] = *(const f32x4*)(b + 8 * (lane + 64 * j)); bv[2 * j + 1] = *(const f32x4*)(b + 8 * (lane + 64 * j) + 4);
;     }
;     u32x4 cur[2], nxt[2];
;     if (gw < T_TOK) {
; #pragma unroll
;         for (int j = 0; j < 2; ++j) cur[j] = *(const u32x4*)(y + (size_t)gw * DM + 8 * (lane + 64 * j));
;     }
;     for (int row = gw; row < T_TOK; row += nw) {
.LBB0_721:
	s_or_b64 exec, exec, s[0:1]
	s_waitcnt lgkmcnt(0)
	s_barrier
	s_mov_b64 s[10:11], exec
	v_readlane_b32 s0, v253, 14
	v_readlane_b32 s1, v253, 15
	s_and_b64 s[0:1], s[10:11], s[0:1]
	s_mov_b64 exec, s[0:1]
	s_cbranch_execz .LBB0_726
	global_load_dwordx4 v[2:5], v197, s[84:85] offset:16
	global_load_dwordx4 v[6:9], v197, s[86:87] offset:16
	global_load_dwordx4 v[10:13], v197, s[84:85]
	global_load_dwordx4 v[14:17], v197, s[86:87]
	global_load_dwordx4 v[18:21], v197, s[84:85] offset:2064
	global_load_dwordx4 v[22:25], v197, s[86:87] offset:2064
	global_load_dwordx4 v[26:29], v197, s[84:85] offset:2048
	global_load_dwordx4 v[30:33], v197, s[86:87] offset:2048
	v_lshlrev_b64 v[34:35], 11, v[170:171]
	v_lshl_add_u64 v[50:51], s[90:91], 0, v[34:35]
	v_mov_b32_e32 v149, 0
	v_lshl_add_u64 v[34:35], v[50:51], 0, v[148:149]
	global_load_dwordx4 v[42:45], v[34:35], off
	global_load_dwordx4 v[46:49], v[34:35], off offset:1024
	s_ashr_i32 s27, s26, 31
	v_lshlrev_b64 v[34:35], 11, v[146:147]
	v_lshlrev_b32_e32 v52, 4, v172
	v_mov_b32_e32 v53, v149
	s_lshl_b64 s[12:13], s[26:27], 11
	v_lshl_add_u64 v[54:55], s[90:91], 0, v[34:35]
	s_mov_b64 s[14:15], 0
	s_mov_b32 s18, 0x10000
	s_mov_b32 s19, 0xffff
	v_mov_b32_e32 v1, 0x3727c5ac
	s_mov_b32 s20, 0x800000
	s_brev_b32 s21, 24
	v_mov_b32_e32 v56, v170
	s_waitcnt vmcnt(0)
	s_branch .LBB0_724
; DI unsigned pk_bf16(float a, float b) { f32x2 f = {a, b}; return __builtin_bit_cast(unsigned, __builtin_convertvector(f, bf16x2_t)); }
; DI float bf_lo(unsigned u) { return __uint_as_float(u << 16); }
; DI float bf_hi(unsigned u) { return __uint_as_float(u & 0xffff0000u); }
; DI void ln_phase(const bf16_t* __restrict__ y, const float* __restrict__ g, const float* __restrict__ b, bf16_t* __restrict__ xo, float* __restrict__ xf = nullptr) {
;     ...
;     for (int row = gw; row < T_TOK; row += nw) {
;         if (row + nw < T_TOK) {
; #pragma unroll
;             for (int j = 0; j < 2; ++j) nxt[j] = *(const u32x4*)(y + (size_t)(row + nw) * DM + 8 * (lane + 64 * j));
;         }
;         f32x4 v[4];
; #pragma unroll
;         for (int j = 0; j < 2; ++j) {
;             v[2 * j].x = bf_lo(cur[j].x); v[2 * j].y = bf_hi(cur[j].x); v[2 * j].z = bf_lo(cur[j].y); v[2 * j].w = bf_hi(cur[j].y);
;             v[2 * j + 1].x = bf_lo(cur[j].z); v[2 * j + 1].y = bf_hi(cur[j].z); v[2 * j + 1].z = bf_lo(cur[j].w); v[2 * j + 1].w = bf_hi(cur[j].w);
;         }
;         float s = 0.f;
; #pragma unroll
;         for (int i = 0; i < 4; ++i) s += (v[i].x + v[i].y) + (v[i].z + v[i].w);
;         const float mu = wave_sum(s) * (1.0f / DM);
;         float q = 0.f;
; #pragma unroll
;         for (int i = 0; i < 4; ++i) { const f32x4 d = v[i] - mu; q += (d.x * d.x + d.y * d.y) + (d.z * d.z + d.w * d.w); }
;         const float rstd = rsqrtf(wave_sum(q) * (1.0f / DM) + LN_EPS);
; #pragma unroll
;         for (int j = 0; j < 2; ++j) {
;             const f32x4 o0 = (v[2 * j] - mu) * rstd * gv[2 * j] + bv[2 * j], o1 = (v[2 * j + 1] - mu) * rstd * gv[2 * j + 1] + bv[2 * j + 1];
;             const size_t off = (size_t)row * DM + 8 * (lane + 64 * j);
;             if (xf) { *(f32x4*)(xf + off) = o0; *(f32x4*)(xf + off + 4) = o1; }
;             if (xo) { u32x4 wv = {pk_bf16(o0.x, o0.y), pk_bf16(o0.z, o0.w), pk_bf16(o1.x, o1.y), pk_bf16(o1.z, o1.w)}; *(u32x4*)(xo + off) = wv; }
;         }
; #pragma unroll
;         for (int j = 0; j < 2; ++j) cur[j] = nxt[j];
;     }
.LBB0_723:
	s_or_b64 exec, exec, s[16:17]
	v_lshlrev_b32_e32 v67, 16, v43
	v_lshlrev_b32_e32 v66, 16, v42
	v_and_b32_e32 v43, 0xffff0000, v43
	v_and_b32_e32 v42, 0xffff0000, v42
	v_pk_add_f32 v[68:69], v[66:67], v[42:43]
	v_lshlrev_b32_e32 v62, 16, v49
	v_and_b32_e32 v64, 0xffff0000, v49
	v_add_f32_e32 v49, v68, v69
	v_lshlrev_b32_e32 v69, 16, v45
	v_lshlrev_b32_e32 v68, 16, v44
	v_and_b32_e32 v45, 0xffff0000, v45
	v_and_b32_e32 v44, 0xffff0000, v44
	v_pk_add_f32 v[70:71], v[68:69], v[44:45]
	v_lshlrev_b32_e32 v58, 16, v46
	v_and_b32_e32 v59, 0xffff0000, v46
	v_lshlrev_b32_e32 v46, 16, v47
	v_and_b32_e32 v47, 0xffff0000, v47
	v_pk_add_f32 v[70:71], v[70:71], v[70:71] op_sel_hi:[0,1]
	v_lshlrev_b32_e32 v60, 16, v48
	v_and_b32_e32 v48, 0xffff0000, v48
	v_add_f32_e32 v65, 0, v49
	v_add_f32_e32 v61, v58, v59
	v_add_f32_e32 v49, v46, v47
	v_mov_b32_e32 v63, v71
	v_pk_add_f32 v[72:73], v[60:61], v[48:49]
	v_pk_add_f32 v[70:71], v[62:63], v[64:65]
	s_and_b64 s[16:17], exec, vcc
	v_pk_add_f32 v[70:71], v[72:73], v[70:71]
	s_or_b64 s[14:15], s[16:17], s[14:15]
	v_add_f32_e32 v49, v70, v71
	ds_bpermute_b32 v57, v173, v49
	v_lshl_add_u64 v[54:55], v[54:55], 0, s[12:13]
	s_waitcnt lgkmcnt(0)
	v_add_f32_e32 v49, v49, v57
	ds_bpermute_b32 v57, v175, v49
	s_waitcnt lgkmcnt(0)
	v_add_f32_e32 v49, v49, v57
	ds_bpermute_b32 v57, v192, v49
	s_waitcnt lgkmcnt(0)
	v_add_f32_e32 v49, v49, v57
	ds_bpermute_b32 v57, v193, v49
	s_waitcnt lgkmcnt(0)
	v_add_f32_e32 v49, v49, v57
	ds_bpermute_b32 v57, v194, v49
	s_waitcnt lgkmcnt(0)
	v_add_f32_e32 v49, v49, v57
	ds_bpermute_b32 v57, v195, v49
	s_waitcnt lgkmcnt(0)
	v_add_f32_e32 v49, v49, v57
	v_fmac_f32_e32 v42, 0xba800000, v49
	v_fmac_f32_e32 v43, 0xba800000, v49
	v_fmac_f32_e32 v67, 0xba800000, v49
	v_fmac_f32_e32 v66, 0xba800000, v49
	v_mov_b32_e32 v70, v67
	v_mov_b32_e32 v71, v43
	v_mov_b32_e32 v67, v42
	v_pk_mul_f32 v[72:73], v[70:71], v[70:71]
	v_pk_mul_f32 v[42:43], v[66:67], v[66:67]
	v_fmac_f32_e32 v44, 0xba800000, v49
	v_pk_mov_b32 v[74:75], v[42:43], v[72:73] op_sel:[1,0]
	v_mov_b32_e32 v43, v73
	v_fmac_f32_e32 v45, 0xba800000, v49
	v_fmac_f32_e32 v69, 0xba800000, v49
	v_pk_add_f32 v[42:43], v[74:75], v[42:43]
	v_fmac_f32_e32 v68, 0xba800000, v49
	v_mov_b32_e32 v72, v69
	v_mov_b32_e32 v73, v45
	v_mov_b32_e32 v69, v44
	v_pk_add_f32 v[42:43], v[42:43], v[42:43] op_sel_hi:[0,1]
	v_pk_mul_f32 v[74:75], v[72:73], v[72:73]
	v_pk_mul_f32 v[44:45], v[68:69], v[68:69]
	v_fmac_f32_e32 v58, 0xba800000, v49
	v_pk_mov_b32 v[76:77], v[44:45], v[74:75] op_sel:[1,0]
	v_mov_b32_e32 v45, v75
	v_fmac_f32_e32 v59, 0xba800000, v49
	v_fmac_f32_e32 v46, 0xba800000, v49
	v_mul_f32_e32 v42, v58, v58
	v_pk_add_f32 v[44:45], v[76:77], v[44:45]
	v_fmac_f32_e32 v47, 0xba800000, v49
	v_pk_fma_f32 v[74:75], v[58:59], v[58:59], v[42:43] op_sel_hi:[1,1,0]
	v_mul_f32_e32 v42, v46, v46
	v_pk_add_f32 v[44:45], v[44:45], v[44:45] op_sel_hi:[0,1]
	v_pk_fma_f32 v[76:77], v[46:47], v[46:47], v[42:43] op_sel_hi:[1,1,0]
	v_fmac_f32_e32 v64, 0xba800000, v49
	v_fmac_f32_e32 v62, 0xba800000, v49
	v_fmac_f32_e32 v48, 0xba800000, v49
	v_fmac_f32_e32 v60, 0xba800000, v49
	v_mul_f32_e32 v74, v60, v60
	v_mul_f32_e32 v76, v48, v48
	v_mul_f32_e32 v42, v62, v62
	v_mul_f32_e32 v44, v64, v64
	v_pk_add_f32 v[74:75], v[74:75], v[76:77]
	v_pk_add_f32 v[42:43], v[42:43], v[44:45]
	v_mov_b32_e32 v61, v48
	v_pk_add_f32 v[42:43], v[74:75], v[42:43]
	v_mov_b32_e32 v63, v64
	v_add_f32_e32 v42, v42, v43
	ds_bpermute_b32 v43, v173, v42
	s_waitcnt lgkmcnt(0)
	v_add_f32_e32 v42, v42, v43
	ds_bpermute_b32 v43, v175, v42
	s_waitcnt lgkmcnt(0)
	v_add_f32_e32 v42, v42, v43
	ds_bpermute_b32 v43, v192, v42
	s_waitcnt lgkmcnt(0)
	v_add_f32_e32 v42, v42, v43
	ds_bpermute_b32 v43, v193, v42
	s_waitcnt lgkmcnt(0)
	v_add_f32_e32 v42, v42, v43
	ds_bpermute_b32 v43, v194, v42
	s_waitcnt lgkmcnt(0)
	v_add_f32_e32 v42, v42, v43
	ds_bpermute_b32 v43, v195, v42
	s_waitcnt lgkmcnt(0)
	v_add_f32_e32 v42, v42, v43
	v_fmamk_f32 v42, v42, 0x3a800000, v1
	v_mul_f32_e32 v43, 0x4b800000, v42
	v_cmp_gt_f32_e64 s[0:1], s20, v42
	s_nop 1
	v_cndmask_b32_e64 v42, v42, v43, s[0:1]
	v_rsq_f32_e32 v42, v42
	s_nop 0
	v_mul_f32_e32 v43, 0x45800000, v42
	v_cndmask_b32_e64 v74, v42, v43, s[0:1]
	v_pk_mul_f32 v[42:43], v[66:67], v[74:75] op_sel_hi:[1,0]
	v_pk_mul_f32 v[44:45], v[70:71], v[74:75] op_sel_hi:[1,0]
	v_pk_mul_f32 v[66:67], v[68:69], v[74:75] op_sel_hi:[1,0]
	v_pk_fma_f32 v[44:45], v[12:13], v[44:45], v[16:17]
	v_pk_fma_f32 v[42:43], v[10:11], v[42:43], v[14:15]
	v_pk_fma_f32 v[66:67], v[2:3], v[66:67], v[6:7]
	v_pk_mul_f32 v[68:69], v[72:73], v[74:75] op_sel_hi:[1,0]
	v_cvt_pk_bf16_f32 v42, v42, v43
	v_cvt_pk_bf16_f32 v43, v44, v45
	v_cvt_pk_bf16_f32 v44, v66, v67
	v_lshl_add_u64 v[66:67], v[50:51], 0, v[52:53]
	v_pk_fma_f32 v[68:69], v[4:5], v[68:69], v[8:9]
	v_add_co_u32_e32 v66, vcc, s21, v66
	v_cvt_pk_bf16_f32 v45, v68, v69
	s_nop 0
	v_addc_co_u32_e32 v67, vcc, 0, v67, vcc
	global_store_dwordx4 v[66:67], v[42:45], off
	v_pk_mul_f32 v[48:49], v[62:63], v[74:75] op_sel_hi:[1,0]
	v_lshl_add_u64 v[50:51], v[50:51], 0, s[12:13]
	v_pk_mul_f32 v[42:43], v[58:59], v[74:75] op_sel_hi:[1,0]
	v_pk_mul_f32 v[44:45], v[46:47], v[74:75] op_sel_hi:[1,0]
	v_pk_mul_f32 v[46:47], v[60:61], v[74:75] op_sel_hi:[1,0]
	v_pk_fma_f32 v[44:45], v[28:29], v[44:45], v[32:33]
	v_pk_fma_f32 v[42:43], v[26:27], v[42:43], v[30:31]
	v_pk_fma_f32 v[48:49], v[20:21], v[48:49], v[24:25]
	v_pk_fma_f32 v[46:47], v[18:19], v[46:47], v[22:23]
	v_cvt_pk_bf16_f32 v42, v42, v43
	v_cvt_pk_bf16_f32 v43, v44, v45
	v_cvt_pk_bf16_f32 v44, v46, v47
	v_cvt_pk_bf16_f32 v45, v48, v49
	global_store_dwordx4 v[66:67], v[42:45], off offset:1024
	s_waitcnt vmcnt(2)
	v_mov_b32_e32 v46, v34
	v_mov_b32_e32 v47, v35
	v_mov_b32_e32 v42, v38
	v_mov_b32_e32 v43, v39
	v_mov_b32_e32 v44, v40
	v_mov_b32_e32 v45, v41
	v_mov_b32_e32 v48, v36
	v_mov_b32_e32 v49, v37
	s_andn2_b64 exec, exec, s[14:15]
	s_cbranch_execz .LBB0_726

; DI void ln_phase(const bf16_t* __restrict__ y, const float* __restrict__ g, const float* __restrict__ b, bf16_t* __restrict__ xo, float* __restrict__ xf = nullptr) {
;     const int lane = threadIdx.x & 63, w = threadIdx.x >> 6;
;     const int gw = blockIdx.x * 4 + w, nw = gridDim.x * 4;
;     f32x4 gv[4], bv[4];
; #pragma unroll
;     for (int j = 0; j < 2; ++j) {
;         gv[2 * j] = *(const f32x4*)(g + 8 * (lane + 64 * j)); gv[2 * j + 1] = *(const f32x4*)(g + 8 * (lane + 64 * j) + 4);
;         bv[2 * j] = *(const f32x4*)(b + 8 * (lane + 64 * j)); bv[2 * j + 1] = *(const f32x4*)(b + 8 * (lane + 64 * j) + 4);
;     }
;     u32x4 cur[2], nxt[2];
;     if (gw < T_TOK) {
; #pragma unroll
;         for (int j = 0; j < 2; ++j) cur[j] = *(const u32x4*)(y + (size_t)gw * DM + 8 * (lane + 64 * j));
;     }
;     for (int row = gw; row < T_TOK; row += nw) {
.LBB0_1045:
	s_or_b64 exec, exec, s[0:1]
	s_waitcnt lgkmcnt(0)
	v_or_b32_e32 v0, 0x200, v151
	v_mov_b32_e32 v49, 0
	v_lshlrev_b32_e32 v186, 2, v0
	s_barrier
	s_mov_b64 s[10:11], exec
	v_readlane_b32 s0, v253, 14
	v_readlane_b32 s1, v253, 15
	s_and_b64 s[0:1], s[10:11], s[0:1]
	s_mov_b64 exec, s[0:1]
	s_cbranch_execz .LBB0_1050
	s_add_u32 s0, s48, 0x1000
	s_addc_u32 s1, s49, 0
	s_add_u32 s12, s50, 0x1000
	s_addc_u32 s13, s51, 0
	global_load_dwordx4 v[0:3], v197, s[0:1] offset:16
	global_load_dwordx4 v[4:7], v197, s[0:1]
	global_load_dwordx4 v[8:11], v197, s[12:13] offset:16
	global_load_dwordx4 v[12:15], v197, s[12:13]
	global_load_dwordx4 v[16:19], v186, s[0:1] offset:16
	global_load_dwordx4 v[20:23], v186, s[0:1]
	global_load_dwordx4 v[24:27], v186, s[12:13] offset:16
	global_load_dwordx4 v[28:31], v186, s[12:13]
	v_lshlrev_b64 v[32:33], 11, v[170:171]
	v_lshl_add_u64 v[50:51], s[90:91], 0, v[32:33]
	v_mov_b32_e32 v149, v49
	v_lshl_add_u64 v[32:33], v[50:51], 0, v[148:149]
	global_load_dwordx4 v[40:43], v[32:33], off
	global_load_dwordx4 v[44:47], v[32:33], off offset:1024
	s_ashr_i32 s27, s26, 31
	v_lshlrev_b64 v[32:33], 11, v[146:147]
	v_lshlrev_b32_e32 v48, 4, v172
	s_lshl_b64 s[12:13], s[26:27], 11
	v_lshl_add_u64 v[52:53], s[90:91], 0, v[32:33]
	s_mov_b64 s[14:15], 0
	s_mov_b32 s18, 0x10000
	s_mov_b32 s19, 0xffff
	v_mov_b32_e32 v54, 0x3727c5ac
	s_mov_b32 s20, 0x800000
	s_brev_b32 s21, 20
	v_mov_b32_e32 v55, v170
	s_waitcnt vmcnt(0)
	s_branch .LBB0_1048
; DI unsigned pk_bf16(float a, float b) { f32x2 f = {a, b}; return __builtin_bit_cast(unsigned, __builtin_convertvector(f, bf16x2_t)); }
; DI float bf_lo(unsigned u) { return __uint_as_float(u << 16); }
; DI float bf_hi(unsigned u) { return __uint_as_float(u & 0xffff0000u); }
; DI void ln_phase(const bf16_t* __restrict__ y, const float* __restrict__ g, const float* __restrict__ b, bf16_t* __restrict__ xo, float* __restrict__ xf = nullptr) {
;     ...
;     for (int row = gw; row < T_TOK; row += nw) {
;         if (row + nw < T_TOK) {
; #pragma unroll
;             for (int j = 0; j < 2; ++j) nxt[j] = *(const u32x4*)(y + (size_t)(row + nw) * DM + 8 * (lane + 64 * j));
;         }
;         f32x4 v[4];
; #pragma unroll
;         for (int j = 0; j < 2; ++j) {
;             v[2 * j].x = bf_lo(cur[j].x); v[2 * j].y = bf_hi(cur[j].x); v[2 * j].z = bf_lo(cur[j].y); v[2 * j].w = bf_hi(cur[j].y);
;             v[2 * j + 1].x = bf_lo(cur[j].z); v[2 * j + 1].y = bf_hi(cur[j].z); v[2 * j + 1].z = bf_lo(cur[j].w); v[2 * j + 1].w = bf_hi(cur[j].w);
;         }
;         float s = 0.f;
; #pragma unroll
;         for (int i = 0; i < 4; ++i) s += (v[i].x + v[i].y) + (v[i].z + v[i].w);
;         const float mu = wave_sum(s) * (1.0f / DM);
;         float q = 0.f;
; #pragma unroll
;         for (int i = 0; i < 4; ++i) { const f32x4 d = v[i] - mu; q += (d.x * d.x + d.y * d.y) + (d.z * d.z + d.w * d.w); }
;         const float rstd = rsqrtf(wave_sum(q) * (1.0f / DM) + LN_EPS);
; #pragma unroll
;         for (int j = 0; j < 2; ++j) {
;             const f32x4 o0 = (v[2 * j] - mu) * rstd * gv[2 * j] + bv[2 * j], o1 = (v[2 * j + 1] - mu) * rstd * gv[2 * j + 1] + bv[2 * j + 1];
;             const size_t off = (size_t)row * DM + 8 * (lane + 64 * j);
;             if (xf) { *(f32x4*)(xf + off) = o0; *(f32x4*)(xf + off + 4) = o1; }
;             if (xo) { u32x4 wv = {pk_bf16(o0.x, o0.y), pk_bf16(o0.z, o0.w), pk_bf16(o1.x, o1.y), pk_bf16(o1.z, o1.w)}; *(u32x4*)(xo + off) = wv; }
;         }
; #pragma unroll
;         for (int j = 0; j < 2; ++j) cur[j] = nxt[j];
;     }
.LBB0_1047:
	s_or_b64 exec, exec, s[16:17]
	v_lshlrev_b32_e32 v65, 16, v41
	v_lshlrev_b32_e32 v64, 16, v40
	v_and_b32_e32 v41, 0xffff0000, v41
	v_and_b32_e32 v40, 0xffff0000, v40
	v_pk_add_f32 v[66:67], v[64:65], v[40:41]
	v_lshlrev_b32_e32 v60, 16, v47
	v_and_b32_e32 v62, 0xffff0000, v47
	v_add_f32_e32 v47, v66, v67
	v_lshlrev_b32_e32 v67, 16, v43
	v_lshlrev_b32_e32 v66, 16, v42
	v_and_b32_e32 v43, 0xffff0000, v43
	v_and_b32_e32 v42, 0xffff0000, v42
	v_pk_add_f32 v[68:69], v[66:67], v[42:43]
	v_lshlrev_b32_e32 v56, 16, v44
	v_and_b32_e32 v57, 0xffff0000, v44
	v_lshlrev_b32_e32 v44, 16, v45
	v_and_b32_e32 v45, 0xffff0000, v45
	v_pk_add_f32 v[68:69], v[68:69], v[68:69] op_sel_hi:[0,1]
	v_lshlrev_b32_e32 v58, 16, v46
	v_and_b32_e32 v46, 0xffff0000, v46
	v_add_f32_e32 v63, 0, v47
	v_add_f32_e32 v59, v56, v57
	v_add_f32_e32 v47, v44, v45
	v_mov_b32_e32 v61, v69
	v_pk_add_f32 v[70:71], v[58:59], v[46:47]
	v_pk_add_f32 v[68:69], v[60:61], v[62:63]
	s_and_b64 s[16:17], exec, vcc
	v_pk_add_f32 v[68:69], v[70:71], v[68:69]
	s_or_b64 s[14:15], s[16:17], s[14:15]
	v_add_f32_e32 v47, v68, v69
	ds_bpermute_b32 v59, v173, v47
	v_lshl_add_u64 v[52:53], v[52:53], 0, s[12:13]
	s_waitcnt lgkmcnt(0)
	v_add_f32_e32 v47, v47, v59
	ds_bpermute_b32 v59, v175, v47
	s_waitcnt lgkmcnt(0)
	v_add_f32_e32 v47, v47, v59
	ds_bpermute_b32 v59, v192, v47
	s_waitcnt lgkmcnt(0)
	v_add_f32_e32 v47, v47, v59
	ds_bpermute_b32 v59, v193, v47
	s_waitcnt lgkmcnt(0)
	v_add_f32_e32 v47, v47, v59
	ds_bpermute_b32 v59, v194, v47
	s_waitcnt lgkmcnt(0)
	v_add_f32_e32 v47, v47, v59
	ds_bpermute_b32 v59, v195, v47
	s_waitcnt lgkmcnt(0)
	v_add_f32_e32 v47, v47, v59
	v_fmac_f32_e32 v40, 0xba800000, v47
	v_fmac_f32_e32 v41, 0xba800000, v47
	v_fmac_f32_e32 v65, 0xba800000, v47
	v_fmac_f32_e32 v64, 0xba800000, v47
	v_mov_b32_e32 v68, v65
	v_mov_b32_e32 v69, v41
	v_mov_b32_e32 v65, v40
	v_pk_mul_f32 v[70:71], v[68:69], v[68:69]
	v_pk_mul_f32 v[40:41], v[64:65], v[64:65]
	v_fmac_f32_e32 v42, 0xba800000, v47
	v_pk_mov_b32 v[72:73], v[40:41], v[70:71] op_sel:[1,0]
	v_mov_b32_e32 v41, v71
	v_fmac_f32_e32 v43, 0xba800000, v47
	v_fmac_f32_e32 v67, 0xba800000, v47
	v_pk_add_f32 v[40:41], v[72:73], v[40:41]
	v_fmac_f32_e32 v66, 0xba800000, v47
	v_mov_b32_e32 v70, v67
	v_mov_b32_e32 v71, v43
	v_mov_b32_e32 v67, v42
	v_pk_add_f32 v[40:41], v[40:41], v[40:41] op_sel_hi:[0,1]
	v_pk_mul_f32 v[72:73], v[70:71], v[70:71]
	v_pk_mul_f32 v[42:43], v[66:67], v[66:67]
	v_fmac_f32_e32 v56, 0xba800000, v47
	v_pk_mov_b32 v[74:75], v[42:43], v[72:73] op_sel:[1,0]
	v_mov_b32_e32 v43, v73
	v_fmac_f32_e32 v57, 0xba800000, v47
	v_fmac_f32_e32 v44, 0xba800000, v47
	v_mul_f32_e32 v40, v56, v56
	v_pk_add_f32 v[42:43], v[74:75], v[42:43]
	v_fmac_f32_e32 v45, 0xba800000, v47
	v_pk_fma_f32 v[72:73], v[56:57], v[56:57], v[40:41] op_sel_hi:[1,1,0]
	v_mul_f32_e32 v40, v44, v44
	v_pk_add_f32 v[42:43], v[42:43], v[42:43] op_sel_hi:[0,1]
	v_pk_fma_f32 v[74:75], v[44:45], v[44:45], v[40:41] op_sel_hi:[1,1,0]
	v_fmac_f32_e32 v62, 0xba800000, v47
	v_fmac_f32_e32 v60, 0xba800000, v47
	v_fmac_f32_e32 v46, 0xba800000, v47
	v_fmac_f32_e32 v58, 0xba800000, v47
	v_mul_f32_e32 v72, v58, v58
	v_mul_f32_e32 v74, v46, v46
	v_mul_f32_e32 v40, v60, v60
	v_mul_f32_e32 v42, v62, v62
	v_pk_add_f32 v[72:73], v[72:73], v[74:75]
	v_pk_add_f32 v[40:41], v[40:41], v[42:43]
	v_mov_b32_e32 v59, v46
	v_pk_add_f32 v[40:41], v[72:73], v[40:41]
	v_mov_b32_e32 v61, v62
	v_add_f32_e32 v40, v40, v41
	ds_bpermute_b32 v41, v173, v40
	s_waitcnt lgkmcnt(0)
	v_add_f32_e32 v40, v40, v41
	ds_bpermute_b32 v41, v175, v40
	s_waitcnt lgkmcnt(0)
	v_add_f32_e32 v40, v40, v41
	ds_bpermute_b32 v41, v192, v40
	s_waitcnt lgkmcnt(0)
	v_add_f32_e32 v40, v40, v41
	ds_bpermute_b32 v41, v193, v40
	s_waitcnt lgkmcnt(0)
	v_add_f32_e32 v40, v40, v41
	ds_bpermute_b32 v41, v194, v40
	s_waitcnt lgkmcnt(0)
	v_add_f32_e32 v40, v40, v41
	ds_bpermute_b32 v41, v195, v40
	s_waitcnt lgkmcnt(0)
	v_add_f32_e32 v40, v40, v41
	v_fmamk_f32 v40, v40, 0x3a800000, v54
	v_mul_f32_e32 v41, 0x4b800000, v40
	v_cmp_gt_f32_e64 s[0:1], s20, v40
	s_nop 1
	v_cndmask_b32_e64 v40, v40, v41, s[0:1]
	v_rsq_f32_e32 v40, v40
	s_nop 0
	v_mul_f32_e32 v41, 0x45800000, v40
	v_cndmask_b32_e64 v72, v40, v41, s[0:1]
	v_pk_mul_f32 v[40:41], v[64:65], v[72:73] op_sel_hi:[1,0]
	v_pk_mul_f32 v[42:43], v[68:69], v[72:73] op_sel_hi:[1,0]
	v_pk_mul_f32 v[64:65], v[66:67], v[72:73] op_sel_hi:[1,0]
	v_pk_fma_f32 v[42:43], v[6:7], v[42:43], v[14:15]
	v_pk_fma_f32 v[40:41], v[4:5], v[40:41], v[12:13]
	v_pk_fma_f32 v[64:65], v[0:1], v[64:65], v[8:9]
	v_pk_mul_f32 v[66:67], v[70:71], v[72:73] op_sel_hi:[1,0]
	v_cvt_pk_bf16_f32 v40, v40, v41
	v_cvt_pk_bf16_f32 v41, v42, v43
	v_cvt_pk_bf16_f32 v42, v64, v65
	v_lshl_add_u64 v[64:65], v[50:51], 0, v[48:49]
	v_pk_fma_f32 v[66:67], v[2:3], v[66:67], v[10:11]
	v_add_co_u32_e32 v64, vcc, s21, v64
	v_cvt_pk_bf16_f32 v43, v66, v67
	s_nop 0
	v_addc_co_u32_e32 v65, vcc, 0, v65, vcc
	global_store_dwordx4 v[64:65], v[40:43], off
	v_pk_mul_f32 v[46:47], v[60:61], v[72:73] op_sel_hi:[1,0]
	v_lshl_add_u64 v[50:51], v[50:51], 0, s[12:13]
	v_pk_mul_f32 v[40:41], v[56:57], v[72:73] op_sel_hi:[1,0]
	v_pk_mul_f32 v[42:43], v[44:45], v[72:73] op_sel_hi:[1,0]
	v_pk_mul_f32 v[44:45], v[58:59], v[72:73] op_sel_hi:[1,0]
	v_pk_fma_f32 v[42:43], v[22:23], v[42:43], v[30:31]
	v_pk_fma_f32 v[40:41], v[20:21], v[40:41], v[28:29]
	v_pk_fma_f32 v[46:47], v[18:19], v[46:47], v[26:27]
	v_pk_fma_f32 v[44:45], v[16:17], v[44:45], v[24:25]
	v_cvt_pk_bf16_f32 v40, v40, v41
	v_cvt_pk_bf16_f32 v41, v42, v43
	v_cvt_pk_bf16_f32 v42, v44, v45
	v_cvt_pk_bf16_f32 v43, v46, v47
	global_store_dwordx4 v[64:65], v[40:43], off offset:1024
	s_waitcnt vmcnt(2)
	v_mov_b32_e32 v44, v32
	v_mov_b32_e32 v45, v33
	v_mov_b32_e32 v40, v36
	v_mov_b32_e32 v41, v37
	v_mov_b32_e32 v42, v38
	v_mov_b32_e32 v43, v39
	v_mov_b32_e32 v46, v34
	v_mov_b32_e32 v47, v35
	s_andn2_b64 exec, exec, s[14:15]
	s_cbranch_execz .LBB0_1050

; DI void ln_phase(const bf16_t* __restrict__ y, const float* __restrict__ g, const float* __restrict__ b, bf16_t* __restrict__ xo, float* __restrict__ xf = nullptr) {
;     const int lane = threadIdx.x & 63, w = threadIdx.x >> 6;
;     const int gw = blockIdx.x * 4 + w, nw = gridDim.x * 4;
;     f32x4 gv[4], bv[4];
; #pragma unroll
;     for (int j = 0; j < 2; ++j) {
;         gv[2 * j] = *(const f32x4*)(g + 8 * (lane + 64 * j)); gv[2 * j + 1] = *(const f32x4*)(g + 8 * (lane + 64 * j) + 4);
;         bv[2 * j] = *(const f32x4*)(b + 8 * (lane + 64 * j)); bv[2 * j + 1] = *(const f32x4*)(b + 8 * (lane + 64 * j) + 4);
;     }
;     u32x4 cur[2], nxt[2];
;     if (gw < T_TOK) {
; #pragma unroll
;         for (int j = 0; j < 2; ++j) cur[j] = *(const u32x4*)(y + (size_t)gw * DM + 8 * (lane + 64 * j));
;     }
;     for (int row = gw; row < T_TOK; row += nw) {
;     ...
;         for (int j = 0; j < 2; ++j) cur[j] = nxt[j];
.LBB0_1419:
	s_or_b64 exec, exec, s[0:1]
	v_readlane_b32 s2, v253, 14
	v_readlane_b32 s3, v253, 15
	s_waitcnt lgkmcnt(0)
	s_barrier
	s_and_saveexec_b64 s[0:1], s[2:3]
	s_cbranch_execz .LBB0_1426
	s_add_u32 s0, s84, 0x1000
	s_addc_u32 s1, s85, 0
	s_add_u32 s2, s86, 0x1000
	s_addc_u32 s3, s87, 0
	global_load_dwordx4 v[0:3], v197, s[0:1] offset:16
	global_load_dwordx4 v[4:7], v197, s[0:1]
	global_load_dwordx4 v[8:11], v197, s[2:3] offset:16
	global_load_dwordx4 v[12:15], v197, s[2:3]
	global_load_dwordx4 v[16:19], v186, s[0:1] offset:16
	global_load_dwordx4 v[20:23], v186, s[0:1]
	global_load_dwordx4 v[24:27], v186, s[2:3] offset:16
	global_load_dwordx4 v[28:31], v186, s[2:3]
	v_lshlrev_b64 v[32:33], 11, v[170:171]
	v_lshl_add_u64 v[32:33], s[90:91], 0, v[32:33]
	v_mov_b32_e32 v149, 0
	v_lshl_add_u64 v[32:33], v[32:33], 0, v[148:149]
	global_load_dwordx4 v[40:43], v[32:33], off
	global_load_dwordx4 v[44:47], v[32:33], off offset:1024
	v_lshlrev_b64 v[32:33], 12, v[170:171]
	v_lshl_or_b32 v32, v172, 5, v32
	v_lshl_add_u64 v[32:33], s[88:89], 0, v[32:33]
	s_mov_b64 s[0:1], 0x810
	v_lshl_add_u64 v[48:49], v[32:33], 0, s[0:1]
	v_lshlrev_b64 v[32:33], 11, v[146:147]
	s_cmp_lg_u64 s[88:89], 0
	v_lshl_or_b32 v32, v172, 4, v32
	s_cselect_b64 s[4:5], -1, 0
	s_ashr_i32 s27, s26, 31
	v_lshl_add_u64 v[32:33], s[90:91], 0, v[32:33]
	s_mov_b64 s[0:1], 0x400
	s_mov_b64 s[2:3], 0
	s_lshl_b64 s[6:7], s[26:27], 12
	v_lshl_add_u64 v[50:51], v[32:33], 0, s[0:1]
	s_lshl_b64 s[8:9], s[26:27], 11
	s_mov_b32 s12, 0x10000
	s_mov_b32 s13, 0xffff
	v_mov_b32_e32 v64, 0x3727c5ac
	s_mov_b32 s14, 0x800000
	s_waitcnt vmcnt(0)
	s_branch .LBB0_1422
.Lln4_skip:
	s_waitcnt vmcnt(0)
.LBB0_1421:
	s_and_b64 s[0:1], exec, s[0:1]
	s_or_b64 s[2:3], s[0:1], s[2:3]
	v_lshl_add_u64 v[48:49], v[48:49], 0, s[6:7]
	v_lshl_add_u64 v[50:51], v[50:51], 0, s[8:9]
	v_mov_b32_e32 v40, v36
	v_mov_b32_e32 v41, v37
	v_mov_b32_e32 v42, v38
	v_mov_b32_e32 v43, v39
	v_mov_b32_e32 v44, v32
	v_mov_b32_e32 v45, v33
	v_mov_b32_e32 v46, v34
	s_waitcnt lgkmcnt(0)
	v_mov_b32_e32 v47, v35
	s_andn2_b64 exec, exec, s[2:3]
	s_cbranch_execz .LBB0_1426

; DI unsigned pk_bf16(float a, float b) { f32x2 f = {a, b}; return __builtin_bit_cast(unsigned, __builtin_convertvector(f, bf16x2_t)); }
; DI float bf_lo(unsigned u) { return __uint_as_float(u << 16); }
; DI float bf_hi(unsigned u) { return __uint_as_float(u & 0xffff0000u); }
; DI void ln_phase(const bf16_t* __restrict__ y, const float* __restrict__ g, const float* __restrict__ b, bf16_t* __restrict__ xo, float* __restrict__ xf = nullptr) {
;     ...
;         f32x4 v[4];
; #pragma unroll
;         for (int j = 0; j < 2; ++j) {
;             v[2 * j].x = bf_lo(cur[j].x); v[2 * j].y = bf_hi(cur[j].x); v[2 * j].z = bf_lo(cur[j].y); v[2 * j].w = bf_hi(cur[j].y);
;             v[2 * j + 1].x = bf_lo(cur[j].z); v[2 * j + 1].y = bf_hi(cur[j].z); v[2 * j + 1].z = bf_lo(cur[j].w); v[2 * j + 1].w = bf_hi(cur[j].w);
;         }
;         float s = 0.f;
; #pragma unroll
;         for (int i = 0; i < 4; ++i) s += (v[i].x + v[i].y) + (v[i].z + v[i].w);
;         const float mu = wave_sum(s) * (1.0f / DM);
;         float q = 0.f;
; #pragma unroll
;         for (int i = 0; i < 4; ++i) { const f32x4 d = v[i] - mu; q += (d.x * d.x + d.y * d.y) + (d.z * d.z + d.w * d.w); }
;         const float rstd = rsqrtf(wave_sum(q) * (1.0f / DM) + LN_EPS);
; #pragma unroll
;         for (int j = 0; j < 2; ++j) {
;             const f32x4 o0 = (v[2 * j] - mu) * rstd * gv[2 * j] + bv[2 * j], o1 = (v[2 * j + 1] - mu) * rstd * gv[2 * j + 1] + bv[2 * j + 1];
;             const size_t off = (size_t)row * DM + 8 * (lane + 64 * j);
;             if (xf) { *(f32x4*)(xf + off) = o0; *(f32x4*)(xf + off + 4) = o1; }
;             if (xo) { u32x4 wv = {pk_bf16(o0.x, o0.y), pk_bf16(o0.z, o0.w), pk_bf16(o1.x, o1.y), pk_bf16(o1.z, o1.w)}; *(u32x4*)(xo + off) = wv; }
;         }
.LBB0_1424:
	s_or_b64 exec, exec, s[10:11]
	v_lshlrev_b32_e32 v59, 16, v41
	v_lshlrev_b32_e32 v58, 16, v40
	v_and_b32_e32 v41, 0xffff0000, v41
	v_and_b32_e32 v40, 0xffff0000, v40
	v_pk_add_f32 v[62:63], v[58:59], v[40:41]
	v_lshlrev_b32_e32 v54, 16, v45
	v_and_b32_e32 v55, 0xffff0000, v45
	v_add_f32_e32 v45, v62, v63
	v_lshlrev_b32_e32 v63, 16, v43
	v_lshlrev_b32_e32 v62, 16, v42
	v_and_b32_e32 v43, 0xffff0000, v43
	v_and_b32_e32 v42, 0xffff0000, v42
	v_pk_add_f32 v[66:67], v[62:63], v[42:43]
	v_lshlrev_b32_e32 v56, 16, v44
	v_and_b32_e32 v57, 0xffff0000, v44
	v_pk_add_f32 v[66:67], v[66:67], v[66:67] op_sel_hi:[0,1]
	v_lshlrev_b32_e32 v52, 16, v46
	v_and_b32_e32 v60, 0xffff0000, v46
	v_lshlrev_b32_e32 v44, 16, v47
	v_and_b32_e32 v46, 0xffff0000, v47
	v_add_f32_e32 v47, 0, v45
	v_add_f32_e32 v53, v56, v57
	v_add_f32_e32 v61, v54, v55
	v_mov_b32_e32 v45, v67
	v_pk_add_f32 v[68:69], v[52:53], v[60:61]
	v_pk_add_f32 v[66:67], v[44:45], v[46:47]
	s_andn2_b64 vcc, exec, s[4:5]
	v_pk_add_f32 v[66:67], v[68:69], v[66:67]
	s_nop 0
	v_add_f32_e32 v45, v66, v67
	ds_bpermute_b32 v47, v173, v45
	s_waitcnt lgkmcnt(0)
	v_add_f32_e32 v45, v45, v47
	ds_bpermute_b32 v47, v175, v45
	s_waitcnt lgkmcnt(0)
	v_add_f32_e32 v45, v45, v47
	ds_bpermute_b32 v47, v192, v45
	s_waitcnt lgkmcnt(0)
	v_add_f32_e32 v45, v45, v47
	ds_bpermute_b32 v47, v193, v45
	s_waitcnt lgkmcnt(0)
	v_add_f32_e32 v45, v45, v47
	ds_bpermute_b32 v47, v194, v45
	s_waitcnt lgkmcnt(0)
	v_add_f32_e32 v45, v45, v47
	ds_bpermute_b32 v47, v195, v45
	s_waitcnt lgkmcnt(0)
	v_add_f32_e32 v45, v45, v47
	v_fmac_f32_e32 v41, 0xba800000, v45
	v_fmac_f32_e32 v40, 0xba800000, v45
	v_fmac_f32_e32 v59, 0xba800000, v45
	v_fmac_f32_e32 v58, 0xba800000, v45
	v_mul_f32_e32 v47, v40, v40
	v_mul_f32_e32 v53, v41, v41
	v_fmac_f32_e32 v47, v58, v58
	v_fmac_f32_e32 v53, v59, v59
	v_fmac_f32_e32 v43, 0xba800000, v45
	v_fmac_f32_e32 v42, 0xba800000, v45
	v_add_f32_e32 v47, v47, v53
	v_fmac_f32_e32 v63, 0xba800000, v45
	v_fmac_f32_e32 v62, 0xba800000, v45
	v_mul_f32_e32 v53, v42, v42
	v_mul_f32_e32 v61, v43, v43
	v_fmac_f32_e32 v53, v62, v62
	v_fmac_f32_e32 v61, v63, v63
	v_add_f32_e32 v53, v53, v61
	v_fmac_f32_e32 v55, 0xba800000, v45
	v_fmac_f32_e32 v57, 0xba800000, v45
	v_add_f32_e32 v47, v47, v53
	v_fmac_f32_e32 v54, 0xba800000, v45
	v_fmac_f32_e32 v56, 0xba800000, v45
	v_mul_f32_e32 v53, v57, v57
	v_mul_f32_e32 v61, v55, v55
	v_fmac_f32_e32 v53, v56, v56
	v_fmac_f32_e32 v61, v54, v54
	v_add_f32_e32 v53, v53, v61
	v_fmac_f32_e32 v46, 0xba800000, v45
	v_fmac_f32_e32 v60, 0xba800000, v45
	v_add_f32_e32 v47, v53, v47
	v_fmac_f32_e32 v44, 0xba800000, v45
	v_fmac_f32_e32 v52, 0xba800000, v45
	v_mul_f32_e32 v45, v60, v60
	v_mul_f32_e32 v53, v46, v46
	v_fmac_f32_e32 v45, v52, v52
	v_fmac_f32_e32 v53, v44, v44
	v_add_f32_e32 v45, v45, v53
	v_add_f32_e32 v45, v45, v47
	ds_bpermute_b32 v47, v173, v45
	s_waitcnt lgkmcnt(0)
	v_add_f32_e32 v45, v45, v47
	ds_bpermute_b32 v47, v175, v45
	s_waitcnt lgkmcnt(0)
	v_add_f32_e32 v45, v45, v47
	ds_bpermute_b32 v47, v192, v45
	s_waitcnt lgkmcnt(0)
	v_add_f32_e32 v45, v45, v47
	ds_bpermute_b32 v47, v193, v45
	s_waitcnt lgkmcnt(0)
	v_add_f32_e32 v45, v45, v47
	ds_bpermute_b32 v47, v194, v45
	s_waitcnt lgkmcnt(0)
	v_add_f32_e32 v45, v45, v47
	ds_bpermute_b32 v47, v195, v45
	s_cbranch_vccnz .Lln4_skip
	v_mov_b32_e32 v67, v40
	s_waitcnt lgkmcnt(0)
	v_add_f32_e32 v40, v45, v47
	v_fmamk_f32 v40, v40, 0x3a800000, v64
	v_mul_f32_e32 v45, 0x4b800000, v40
	v_cmp_gt_f32_e32 vcc, s14, v40
	v_mov_b32_e32 v69, v42
	v_mov_b32_e32 v66, v58
	v_cndmask_b32_e32 v40, v40, v45, vcc
	v_rsq_f32_e32 v40, v40
	v_mov_b32_e32 v68, v62
	v_mov_b32_e32 v53, v60
	v_mov_b32_e32 v45, v46
	v_mul_f32_e32 v42, 0x45800000, v40
	v_cndmask_b32_e32 v58, v40, v42, vcc
	v_mov_b32_e32 v42, v63
	v_mov_b32_e32 v40, v59
	v_pk_mul_f32 v[42:43], v[42:43], v[58:59] op_sel_hi:[1,0]
	v_pk_mul_f32 v[66:67], v[66:67], v[58:59] op_sel_hi:[1,0]
	v_pk_mul_f32 v[40:41], v[40:41], v[58:59] op_sel_hi:[1,0]
	v_pk_mul_f32 v[60:61], v[68:69], v[58:59] op_sel_hi:[1,0]
	v_pk_fma_f32 v[62:63], v[2:3], v[42:43], v[10:11]
	v_pk_fma_f32 v[42:43], v[6:7], v[40:41], v[14:15]
	v_pk_fma_f32 v[40:41], v[4:5], v[66:67], v[12:13]
	v_pk_fma_f32 v[60:61], v[0:1], v[60:61], v[8:9]
	global_store_dwordx4 v[48:49], v[40:43], off offset:-2064
	global_store_dwordx4 v[48:49], v[60:63], off offset:-2048
	v_pk_mul_f32 v[52:53], v[52:53], v[58:59] op_sel_hi:[1,0]
	v_pk_mul_f32 v[40:41], v[56:57], v[58:59] op_sel_hi:[1,0]
	v_pk_mul_f32 v[42:43], v[54:55], v[58:59] op_sel_hi:[1,0]
	v_pk_fma_f32 v[40:41], v[20:21], v[40:41], v[28:29]
	v_pk_fma_f32 v[42:43], v[22:23], v[42:43], v[30:31]
	v_pk_mul_f32 v[44:45], v[44:45], v[58:59] op_sel_hi:[1,0]
	s_nop 0
	v_pk_fma_f32 v[46:47], v[18:19], v[44:45], v[26:27]
	v_pk_fma_f32 v[44:45], v[16:17], v[52:53], v[24:25]
	global_store_dwordx4 v[48:49], v[40:43], off offset:-16
	global_store_dwordx4 v[48:49], v[44:47], off
	s_waitcnt vmcnt(4)
	s_branch .LBB0_1421
